# sc1 (write-through) on the P5-tail weight-conversion stores
# baseline (speedup 1.0000x reference)
.LBB0_499:
	s_waitcnt vmcnt(0)
	v_mul_f32_e32 v10, v66, v13
	ds_write2_b32 v16, v12, v10 offset0:140 offset1:206
	s_waitcnt lgkmcnt(0)
	ds_read2_b32 v[16:17], v61 offset0:33 offset1:41
	ds_read2_b32 v[18:19], v61 offset1:8
	ds_read2_b32 v[20:21], v61 offset0:66 offset1:74
	ds_read2_b32 v[22:23], v61 offset0:99 offset1:107
	ds_read2_b32 v[24:25], v61 offset0:132 offset1:140
	ds_read2_b32 v[26:27], v61 offset0:165 offset1:173
	ds_read2_b32 v[28:29], v61 offset0:198 offset1:206
	ds_read2_b32 v[30:31], v61 offset0:231 offset1:239
	v_or_b32_e32 v34, s24, v46
	v_ashrrev_i32_e32 v35, 31, v34
	v_lshl_add_u64 v[32:33], s[22:23], 1, v[8:9]
	v_lshlrev_b64 v[34:35], 11, v[34:35]
	s_waitcnt lgkmcnt(6)
	v_cvt_pk_bf16_f32 v12, v18, v16
	s_waitcnt lgkmcnt(4)
	v_cvt_pk_bf16_f32 v13, v20, v22
	s_waitcnt lgkmcnt(2)
	v_cvt_pk_bf16_f32 v14, v24, v26
	s_waitcnt lgkmcnt(0)
	v_cvt_pk_bf16_f32 v15, v28, v30
	v_lshl_add_u64 v[34:35], v[32:33], 0, v[34:35]
	v_or_b32_e32 v16, s24, v62
	global_store_dwordx4 v[34:35], v[12:15], off sc1
	s_nop 1
	v_cvt_pk_bf16_f32 v12, v19, v17
	v_ashrrev_i32_e32 v17, 31, v16
	v_cvt_pk_bf16_f32 v13, v21, v23
	v_cvt_pk_bf16_f32 v14, v25, v27
	v_cvt_pk_bf16_f32 v15, v29, v31
	v_lshlrev_b64 v[16:17], 11, v[16:17]
	ds_read2_b32 v[18:19], v61 offset0:49 offset1:57
	ds_read2_b32 v[20:21], v61 offset0:16 offset1:24
	ds_read2_b32 v[22:23], v61 offset0:82 offset1:90
	ds_read2_b32 v[24:25], v61 offset0:115 offset1:123
	ds_read2_b32 v[26:27], v61 offset0:148 offset1:156
	ds_read2_b32 v[28:29], v61 offset0:181 offset1:189
	ds_read2_b32 v[30:31], v61 offset0:214 offset1:222
	ds_read2_b32 v[34:35], v61 offset0:247 offset1:255
	v_lshl_add_u64 v[16:17], v[32:33], 0, v[16:17]
	global_store_dwordx4 v[16:17], v[12:15], off sc1
	v_or_b32_e32 v16, s24, v63
	v_ashrrev_i32_e32 v17, 31, v16
	v_lshlrev_b64 v[16:17], 11, v[16:17]
	s_waitcnt lgkmcnt(6)
	v_cvt_pk_bf16_f32 v12, v20, v18
	s_waitcnt lgkmcnt(4)
	v_cvt_pk_bf16_f32 v13, v22, v24
	s_waitcnt lgkmcnt(2)
	v_cvt_pk_bf16_f32 v14, v26, v28
	s_waitcnt lgkmcnt(0)
	v_cvt_pk_bf16_f32 v15, v30, v34
	v_lshl_add_u64 v[16:17], v[32:33], 0, v[16:17]
	global_store_dwordx4 v[16:17], v[12:15], off sc1
	v_or_b32_e32 v16, s24, v64
	v_ashrrev_i32_e32 v17, 31, v16
	v_lshlrev_b64 v[16:17], 11, v[16:17]
	v_cvt_pk_bf16_f32 v12, v21, v19
	v_cvt_pk_bf16_f32 v13, v23, v25
	v_cvt_pk_bf16_f32 v14, v27, v29
	v_cvt_pk_bf16_f32 v15, v31, v35
	v_lshl_add_u64 v[16:17], v[32:33], 0, v[16:17]
	global_store_dwordx4 v[16:17], v[12:15], off sc1
	s_waitcnt lgkmcnt(0)

.LBB0_527:
	s_waitcnt vmcnt(0)
	v_mul_f32_e32 v10, v10, v13
	ds_write2_b32 v12, v17, v10 offset0:140 offset1:206
	s_waitcnt lgkmcnt(0)
	ds_read2_b32 v[16:17], v61 offset0:33 offset1:41
	ds_read2_b32 v[18:19], v61 offset1:8
	ds_read2_b32 v[20:21], v61 offset0:66 offset1:74
	ds_read2_b32 v[22:23], v61 offset0:99 offset1:107
	ds_read2_b32 v[24:25], v61 offset0:132 offset1:140
	ds_read2_b32 v[26:27], v61 offset0:165 offset1:173
	ds_read2_b32 v[28:29], v61 offset0:198 offset1:206
	ds_read2_b32 v[30:31], v61 offset0:231 offset1:239
	s_add_i32 s4, s26, 0x800
	v_or_b32_e32 v34, s4, v46
	v_ashrrev_i32_e32 v35, 31, v34
	v_lshl_add_u64 v[32:33], s[22:23], 1, v[8:9]
	v_lshlrev_b64 v[34:35], 11, v[34:35]
	s_waitcnt lgkmcnt(6)
	v_cvt_pk_bf16_f32 v12, v18, v16
	s_waitcnt lgkmcnt(4)
	v_cvt_pk_bf16_f32 v13, v20, v22
	s_waitcnt lgkmcnt(2)
	v_cvt_pk_bf16_f32 v14, v24, v26
	s_waitcnt lgkmcnt(0)
	v_cvt_pk_bf16_f32 v15, v28, v30
	v_lshl_add_u64 v[34:35], v[32:33], 0, v[34:35]
	v_or_b32_e32 v16, s4, v62
	global_store_dwordx4 v[34:35], v[12:15], off sc1
	s_nop 1
	v_cvt_pk_bf16_f32 v12, v19, v17
	v_ashrrev_i32_e32 v17, 31, v16
	v_cvt_pk_bf16_f32 v13, v21, v23
	v_cvt_pk_bf16_f32 v14, v25, v27
	v_cvt_pk_bf16_f32 v15, v29, v31
	v_lshlrev_b64 v[16:17], 11, v[16:17]
	ds_read2_b32 v[18:19], v61 offset0:49 offset1:57
	ds_read2_b32 v[20:21], v61 offset0:16 offset1:24
	ds_read2_b32 v[22:23], v61 offset0:82 offset1:90
	ds_read2_b32 v[24:25], v61 offset0:115 offset1:123
	ds_read2_b32 v[26:27], v61 offset0:148 offset1:156
	ds_read2_b32 v[28:29], v61 offset0:181 offset1:189
	ds_read2_b32 v[30:31], v61 offset0:214 offset1:222
	ds_read2_b32 v[34:35], v61 offset0:247 offset1:255
	v_lshl_add_u64 v[16:17], v[32:33], 0, v[16:17]
	global_store_dwordx4 v[16:17], v[12:15], off sc1
	v_or_b32_e32 v16, s4, v63
	v_ashrrev_i32_e32 v17, 31, v16
	v_lshlrev_b64 v[16:17], 11, v[16:17]
	s_waitcnt lgkmcnt(6)
	v_cvt_pk_bf16_f32 v12, v20, v18
	s_waitcnt lgkmcnt(4)
	v_cvt_pk_bf16_f32 v13, v22, v24
	s_waitcnt lgkmcnt(2)
	v_cvt_pk_bf16_f32 v14, v26, v28
	s_waitcnt lgkmcnt(0)
	v_cvt_pk_bf16_f32 v15, v30, v34
	v_lshl_add_u64 v[16:17], v[32:33], 0, v[16:17]
	global_store_dwordx4 v[16:17], v[12:15], off sc1
	v_or_b32_e32 v16, s4, v64
	v_ashrrev_i32_e32 v17, 31, v16
	v_lshlrev_b64 v[16:17], 11, v[16:17]
	v_cvt_pk_bf16_f32 v12, v21, v19
	v_cvt_pk_bf16_f32 v13, v23, v25
	v_cvt_pk_bf16_f32 v14, v27, v29
	v_cvt_pk_bf16_f32 v15, v31, v35
	v_lshl_add_u64 v[16:17], v[32:33], 0, v[16:17]
	global_store_dwordx4 v[16:17], v[12:15], off sc1
	s_waitcnt lgkmcnt(0)
	s_mov_b64 s[4:5], 0

.LBB0_555:
	s_waitcnt vmcnt(0)
	v_mul_f32_e32 v10, v10, v18
	ds_write2_b32 v17, v19, v10 offset0:140 offset1:206
	s_waitcnt lgkmcnt(0)
	ds_read2_b32 v[18:19], v61 offset0:33 offset1:41
	ds_read2_b32 v[20:21], v61 offset1:8
	ds_read2_b32 v[22:23], v61 offset0:66 offset1:74
	ds_read2_b32 v[24:25], v61 offset0:99 offset1:107
	ds_read2_b32 v[26:27], v61 offset0:132 offset1:140
	ds_read2_b32 v[28:29], v61 offset0:165 offset1:173
	ds_read2_b32 v[30:31], v61 offset0:198 offset1:206
	ds_read2_b32 v[32:33], v61 offset0:231 offset1:239
	s_add_i32 s4, s24, 0x1000
	v_or_b32_e32 v36, s4, v46
	v_ashrrev_i32_e32 v37, 31, v36
	v_lshl_add_u64 v[34:35], s[22:23], 1, v[8:9]
	v_lshlrev_b64 v[36:37], 11, v[36:37]
	s_waitcnt lgkmcnt(6)
	v_cvt_pk_bf16_f32 v14, v20, v18
	s_waitcnt lgkmcnt(4)
	v_cvt_pk_bf16_f32 v15, v22, v24
	s_waitcnt lgkmcnt(2)
	v_cvt_pk_bf16_f32 v16, v26, v28
	s_waitcnt lgkmcnt(0)
	v_cvt_pk_bf16_f32 v17, v30, v32
	v_lshl_add_u64 v[36:37], v[34:35], 0, v[36:37]
	v_or_b32_e32 v18, s4, v62
	global_store_dwordx4 v[36:37], v[14:17], off sc1
	s_nop 1
	v_cvt_pk_bf16_f32 v14, v21, v19
	v_ashrrev_i32_e32 v19, 31, v18
	v_cvt_pk_bf16_f32 v15, v23, v25
	v_cvt_pk_bf16_f32 v16, v27, v29
	v_cvt_pk_bf16_f32 v17, v31, v33
	v_lshlrev_b64 v[18:19], 11, v[18:19]
	ds_read2_b32 v[20:21], v61 offset0:49 offset1:57
	ds_read2_b32 v[22:23], v61 offset0:16 offset1:24
	ds_read2_b32 v[24:25], v61 offset0:82 offset1:90
	ds_read2_b32 v[26:27], v61 offset0:115 offset1:123
	ds_read2_b32 v[28:29], v61 offset0:148 offset1:156
	ds_read2_b32 v[30:31], v61 offset0:181 offset1:189
	ds_read2_b32 v[32:33], v61 offset0:214 offset1:222
	ds_read2_b32 v[36:37], v61 offset0:247 offset1:255
	v_lshl_add_u64 v[18:19], v[34:35], 0, v[18:19]
	global_store_dwordx4 v[18:19], v[14:17], off sc1
	v_or_b32_e32 v18, s4, v63
	v_ashrrev_i32_e32 v19, 31, v18
	v_lshlrev_b64 v[18:19], 11, v[18:19]
	s_waitcnt lgkmcnt(6)
	v_cvt_pk_bf16_f32 v14, v22, v20
	s_waitcnt lgkmcnt(4)
	v_cvt_pk_bf16_f32 v15, v24, v26
	s_waitcnt lgkmcnt(2)
	v_cvt_pk_bf16_f32 v16, v28, v30
	s_waitcnt lgkmcnt(0)
	v_cvt_pk_bf16_f32 v17, v32, v36
	v_lshl_add_u64 v[18:19], v[34:35], 0, v[18:19]
	global_store_dwordx4 v[18:19], v[14:17], off sc1
	v_or_b32_e32 v18, s4, v64
	v_ashrrev_i32_e32 v19, 31, v18
	v_lshlrev_b64 v[18:19], 11, v[18:19]
	v_cvt_pk_bf16_f32 v14, v23, v21
	v_cvt_pk_bf16_f32 v15, v25, v27
	v_cvt_pk_bf16_f32 v16, v29, v31
	v_cvt_pk_bf16_f32 v17, v33, v37
	v_lshl_add_u64 v[18:19], v[34:35], 0, v[18:19]
	global_store_dwordx4 v[18:19], v[14:17], off sc1
	s_waitcnt lgkmcnt(0)
	s_mov_b64 s[4:5], 0

.LBB0_581:
	s_waitcnt vmcnt(0)
	v_mul_f32_e32 v10, v10, v17
	ds_write2_b32 v13, v18, v10 offset0:140 offset1:206
	s_waitcnt lgkmcnt(0)
	ds_read2_b32 v[18:19], v61 offset0:33 offset1:41
	ds_read2_b32 v[20:21], v61 offset1:8
	ds_read2_b32 v[22:23], v61 offset0:66 offset1:74
	ds_read2_b32 v[24:25], v61 offset0:99 offset1:107
	ds_read2_b32 v[26:27], v61 offset0:132 offset1:140
	ds_read2_b32 v[28:29], v61 offset0:165 offset1:173
	ds_read2_b32 v[30:31], v61 offset0:198 offset1:206
	ds_read2_b32 v[32:33], v61 offset0:231 offset1:239
	s_add_i32 s4, s24, 0x1000
	v_or_b32_e32 v36, s4, v46
	v_ashrrev_i32_e32 v37, 31, v36
	v_lshl_add_u64 v[34:35], s[22:23], 1, v[8:9]
	v_lshlrev_b64 v[36:37], 11, v[36:37]
	s_waitcnt lgkmcnt(6)
	v_cvt_pk_bf16_f32 v14, v20, v18
	s_waitcnt lgkmcnt(4)
	v_cvt_pk_bf16_f32 v15, v22, v24
	s_waitcnt lgkmcnt(2)
	v_cvt_pk_bf16_f32 v16, v26, v28
	s_waitcnt lgkmcnt(0)
	v_cvt_pk_bf16_f32 v17, v30, v32
	v_lshl_add_u64 v[36:37], v[34:35], 0, v[36:37]
	v_or_b32_e32 v18, s4, v62
	global_store_dwordx4 v[36:37], v[14:17], off sc1
	s_nop 1
	v_cvt_pk_bf16_f32 v14, v21, v19
	v_ashrrev_i32_e32 v19, 31, v18
	v_cvt_pk_bf16_f32 v15, v23, v25
	v_cvt_pk_bf16_f32 v16, v27, v29
	v_cvt_pk_bf16_f32 v17, v31, v33
	v_lshlrev_b64 v[18:19], 11, v[18:19]
	ds_read2_b32 v[20:21], v61 offset0:49 offset1:57
	ds_read2_b32 v[22:23], v61 offset0:16 offset1:24
	ds_read2_b32 v[24:25], v61 offset0:82 offset1:90
	ds_read2_b32 v[26:27], v61 offset0:115 offset1:123
	ds_read2_b32 v[28:29], v61 offset0:148 offset1:156
	ds_read2_b32 v[30:31], v61 offset0:181 offset1:189
	ds_read2_b32 v[32:33], v61 offset0:214 offset1:222
	ds_read2_b32 v[36:37], v61 offset0:247 offset1:255
	v_lshl_add_u64 v[18:19], v[34:35], 0, v[18:19]
	global_store_dwordx4 v[18:19], v[14:17], off sc1
	v_or_b32_e32 v18, s4, v63
	v_ashrrev_i32_e32 v19, 31, v18
	v_lshlrev_b64 v[18:19], 11, v[18:19]
	s_waitcnt lgkmcnt(6)
	v_cvt_pk_bf16_f32 v14, v22, v20
	s_waitcnt lgkmcnt(4)
	v_cvt_pk_bf16_f32 v15, v24, v26
	s_waitcnt lgkmcnt(2)
	v_cvt_pk_bf16_f32 v16, v28, v30
	s_waitcnt lgkmcnt(0)
	v_cvt_pk_bf16_f32 v17, v32, v36
	v_lshl_add_u64 v[18:19], v[34:35], 0, v[18:19]
	global_store_dwordx4 v[18:19], v[14:17], off sc1
	v_or_b32_e32 v18, s4, v64
	v_ashrrev_i32_e32 v19, 31, v18
	v_lshlrev_b64 v[18:19], 11, v[18:19]
	v_cvt_pk_bf16_f32 v14, v23, v21
	v_cvt_pk_bf16_f32 v15, v25, v27
	v_cvt_pk_bf16_f32 v16, v29, v31
	v_cvt_pk_bf16_f32 v17, v33, v37
	v_lshl_add_u64 v[18:19], v[34:35], 0, v[18:19]
	global_store_dwordx4 v[18:19], v[14:17], off sc1
	s_waitcnt lgkmcnt(0)
	s_cbranch_execnz .LBB0_500
	s_branch .LBB0_585

.LBB0_675:
	s_and_b32 s8, s10, 0xffffffc0
	v_or_b32_e32 v22, s8, v2
	v_ashrrev_i32_e32 v23, 31, v22
	s_and_b32 s14, s12, 0x3e0
	v_lshlrev_b64 v[22:23], 12, v[22:23]
	s_lshl_b32 s6, s14, 2
	s_waitcnt lgkmcnt(0)
	v_lshl_add_u64 v[22:23], s[4:5], 0, v[22:23]
	v_lshl_add_u64 v[22:23], v[22:23], 0, s[6:7]
	v_lshl_add_u64 v[22:23], v[22:23], 0, v[4:5]
	v_add_co_u32_e32 v24, vcc, 0x2000, v22
	global_load_dword v21, v[22:23], off
	s_nop 0
	v_addc_co_u32_e32 v25, vcc, 0, v23, vcc
	v_add_co_u32_e32 v26, vcc, 0x4000, v22
	global_load_dword v30, v[24:25], off
	s_nop 0
	v_addc_co_u32_e32 v27, vcc, 0, v23, vcc
	v_add_co_u32_e32 v24, vcc, 0x6000, v22
	s_ashr_i32 s9, s8, 31
	s_nop 0
	v_addc_co_u32_e32 v25, vcc, 0, v23, vcc
	v_add_co_u32_e32 v28, vcc, 0x8000, v22
	global_load_dword v31, v[26:27], off
	global_load_dword v32, v[24:25], off
	v_addc_co_u32_e32 v29, vcc, 0, v23, vcc
	v_add_co_u32_e32 v24, vcc, 0xa000, v22
	v_or_b32_e32 v6, s14, v46
	s_nop 0
	v_addc_co_u32_e32 v25, vcc, 0, v23, vcc
	v_add_co_u32_e32 v26, vcc, 0xc000, v22
	global_load_dword v33, v[28:29], off
	global_load_dword v34, v[24:25], off
	v_addc_co_u32_e32 v27, vcc, 0, v23, vcc
	v_add_co_u32_e32 v24, vcc, 0xe000, v22
	v_lshlrev_b32_e32 v6, 12, v6
	s_nop 0
	v_addc_co_u32_e32 v25, vcc, 0, v23, vcc
	v_add_co_u32_e32 v28, vcc, 0x10000, v22
	global_load_dword v35, v[26:27], off
	global_load_dword v36, v[24:25], off
	v_addc_co_u32_e32 v29, vcc, 0, v23, vcc
	v_add_co_u32_e32 v24, vcc, 0x12000, v22
	s_add_i32 s30, s30, s80
	s_nop 0
	v_addc_co_u32_e32 v25, vcc, 0, v23, vcc
	v_add_co_u32_e32 v26, vcc, 0x14000, v22
	global_load_dword v37, v[28:29], off
	global_load_dword v47, v[24:25], off
	v_addc_co_u32_e32 v27, vcc, 0, v23, vcc
	v_add_co_u32_e32 v24, vcc, 0x16000, v22
	s_add_i32 s10, s10, s11
	s_nop 0
	v_addc_co_u32_e32 v25, vcc, 0, v23, vcc
	v_add_co_u32_e32 v28, vcc, 0x18000, v22
	global_load_dword v48, v[26:27], off
	global_load_dword v49, v[24:25], off
	v_addc_co_u32_e32 v29, vcc, 0, v23, vcc
	v_add_co_u32_e32 v24, vcc, 0x1a000, v22
	s_add_i32 s12, s12, s13
	s_nop 0
	v_addc_co_u32_e32 v25, vcc, 0, v23, vcc
	v_add_co_u32_e32 v26, vcc, 0x1c000, v22
	global_load_dword v50, v[28:29], off
	global_load_dword v51, v[24:25], off
	v_addc_co_u32_e32 v27, vcc, 0, v23, vcc
	v_add_co_u32_e32 v24, vcc, 0x1e000, v22
	s_cmpk_lt_i32 s30, 0x400
	s_nop 0
	v_addc_co_u32_e32 v25, vcc, 0, v23, vcc
	v_add_co_u32_e32 v28, vcc, 0x20000, v22
	global_load_dword v52, v[26:27], off
	global_load_dword v53, v[24:25], off
	v_addc_co_u32_e32 v29, vcc, 0, v23, vcc
	v_add_co_u32_e32 v24, vcc, 0x22000, v22
	s_nop 1
	v_addc_co_u32_e32 v25, vcc, 0, v23, vcc
	v_add_co_u32_e32 v26, vcc, 0x24000, v22
	global_load_dword v54, v[28:29], off
	global_load_dword v55, v[24:25], off
	v_addc_co_u32_e32 v27, vcc, 0, v23, vcc
	v_add_co_u32_e32 v24, vcc, 0x26000, v22
	s_nop 1
	v_addc_co_u32_e32 v25, vcc, 0, v23, vcc
	v_add_co_u32_e32 v28, vcc, 0x28000, v22
	global_load_dword v56, v[26:27], off
	global_load_dword v57, v[24:25], off
	v_addc_co_u32_e32 v29, vcc, 0, v23, vcc
	v_add_co_u32_e32 v24, vcc, 0x2a000, v22
	s_nop 1
	v_addc_co_u32_e32 v25, vcc, 0, v23, vcc
	v_add_co_u32_e32 v26, vcc, 0x2c000, v22
	global_load_dword v58, v[28:29], off
	global_load_dword v59, v[24:25], off
	v_addc_co_u32_e32 v27, vcc, 0, v23, vcc
	v_add_co_u32_e32 v24, vcc, 0x2e000, v22
	s_nop 1
	v_addc_co_u32_e32 v25, vcc, 0, v23, vcc
	v_add_co_u32_e32 v28, vcc, 0x30000, v22
	global_load_dword v60, v[26:27], off
	global_load_dword v61, v[24:25], off
	v_addc_co_u32_e32 v29, vcc, 0, v23, vcc
	v_add_co_u32_e32 v24, vcc, 0x32000, v22
	s_nop 1
	v_addc_co_u32_e32 v25, vcc, 0, v23, vcc
	v_add_co_u32_e32 v26, vcc, 0x34000, v22
	global_load_dword v62, v[28:29], off
	global_load_dword v63, v[24:25], off
	v_addc_co_u32_e32 v27, vcc, 0, v23, vcc
	v_add_co_u32_e32 v24, vcc, 0x36000, v22
	s_nop 1
	v_addc_co_u32_e32 v25, vcc, 0, v23, vcc
	v_add_co_u32_e32 v28, vcc, 0x38000, v22
	global_load_dword v64, v[26:27], off
	global_load_dword v65, v[24:25], off
	v_addc_co_u32_e32 v29, vcc, 0, v23, vcc
	v_add_co_u32_e32 v24, vcc, 0x3a000, v22
	s_nop 1
	v_addc_co_u32_e32 v25, vcc, 0, v23, vcc
	v_add_co_u32_e32 v26, vcc, 0x3c000, v22
	global_load_dword v66, v[28:29], off
	global_load_dword v67, v[24:25], off
	v_addc_co_u32_e32 v27, vcc, 0, v23, vcc
	v_add_co_u32_e32 v22, vcc, 0x3e000, v22
	v_or_b32_e32 v28, s14, v12
	s_nop 0
	v_addc_co_u32_e32 v23, vcc, 0, v23, vcc
	global_load_dword v24, v[26:27], off
	global_load_dword v25, v[22:23], off
	v_or_b32_e32 v26, s14, v10
	v_lshl_add_u64 v[22:23], s[8:9], 1, v[8:9]
	s_waitcnt vmcnt(30)
	ds_write2_b32 v13, v21, v30 offset1:66
	s_waitcnt vmcnt(28)
	ds_write2_b32 v13, v31, v32 offset0:132 offset1:198
	s_waitcnt vmcnt(26)
	ds_write2_b32 v14, v33, v34 offset0:8 offset1:74
	s_waitcnt vmcnt(24)
	ds_write2_b32 v14, v35, v36 offset0:140 offset1:206
	s_waitcnt vmcnt(22)
	ds_write2_b32 v15, v37, v47 offset0:16 offset1:82
	s_waitcnt vmcnt(20)
	ds_write2_b32 v15, v48, v49 offset0:148 offset1:214
	s_waitcnt vmcnt(18)
	ds_write2_b32 v16, v50, v51 offset0:24 offset1:90
	s_waitcnt vmcnt(16)
	ds_write2_b32 v16, v52, v53 offset0:156 offset1:222
	s_waitcnt vmcnt(14)
	ds_write2_b32 v17, v54, v55 offset0:32 offset1:98
	s_waitcnt vmcnt(12)
	ds_write2_b32 v17, v56, v57 offset0:164 offset1:230
	s_waitcnt vmcnt(10)
	ds_write2_b32 v18, v58, v59 offset0:40 offset1:106
	s_waitcnt vmcnt(8)
	ds_write2_b32 v18, v60, v61 offset0:172 offset1:238
	s_waitcnt vmcnt(6)
	ds_write2_b32 v19, v62, v63 offset0:48 offset1:114
	s_waitcnt vmcnt(4)
	ds_write2_b32 v19, v64, v65 offset0:180 offset1:246
	s_waitcnt vmcnt(2)
	ds_write2_b32 v20, v66, v67 offset0:56 offset1:122
	s_waitcnt vmcnt(0)
	ds_write2_b32 v20, v24, v25 offset0:188 offset1:254
	v_or_b32_e32 v27, s14, v11
	v_lshl_add_u64 v[38:39], v[22:23], 0, v[6:7]
	v_lshlrev_b32_e32 v6, 12, v26
	s_waitcnt lgkmcnt(0)
	v_lshl_add_u64 v[40:41], v[22:23], 0, v[6:7]
	v_lshlrev_b32_e32 v6, 12, v27
	v_lshl_add_u64 v[42:43], v[22:23], 0, v[6:7]
	v_lshlrev_b32_e32 v6, 12, v28
	ds_read2_b32 v[26:27], v3 offset0:33 offset1:41
	ds_read2_b32 v[28:29], v3 offset1:8
	ds_read2_b32 v[30:31], v3 offset0:66 offset1:74
	ds_read2_b32 v[32:33], v3 offset0:99 offset1:107
	ds_read2_b32 v[34:35], v3 offset0:132 offset1:140
	ds_read2_b32 v[36:37], v3 offset0:165 offset1:173
	ds_read2_b32 v[48:49], v3 offset0:198 offset1:206
	ds_read2_b32 v[50:51], v3 offset0:231 offset1:239
	ds_read2_b32 v[52:53], v3 offset0:49 offset1:57
	ds_read2_b32 v[54:55], v3 offset0:16 offset1:24
	ds_read2_b32 v[56:57], v3 offset0:82 offset1:90
	ds_read2_b32 v[58:59], v3 offset0:115 offset1:123
	ds_read2_b32 v[60:61], v3 offset0:148 offset1:156
	ds_read2_b32 v[62:63], v3 offset0:181 offset1:189
	ds_read2_b32 v[64:65], v3 offset0:214 offset1:222
	ds_read2_b32 v[66:67], v3 offset0:247 offset1:255
	v_lshl_add_u64 v[44:45], v[22:23], 0, v[6:7]
	s_waitcnt lgkmcnt(14)
	v_cvt_pk_bf16_f32 v22, v28, v26
	s_waitcnt lgkmcnt(12)
	v_cvt_pk_bf16_f32 v23, v30, v32
	s_waitcnt lgkmcnt(10)
	v_cvt_pk_bf16_f32 v24, v34, v36
	s_waitcnt lgkmcnt(8)
	v_cvt_pk_bf16_f32 v25, v48, v50
	v_cvt_pk_bf16_f32 v26, v29, v27
	v_cvt_pk_bf16_f32 v27, v31, v33
	v_cvt_pk_bf16_f32 v28, v35, v37
	v_cvt_pk_bf16_f32 v29, v49, v51
	s_waitcnt lgkmcnt(6)
	v_cvt_pk_bf16_f32 v30, v54, v52
	s_waitcnt lgkmcnt(4)
	v_cvt_pk_bf16_f32 v31, v56, v58
	s_waitcnt lgkmcnt(2)
	v_cvt_pk_bf16_f32 v32, v60, v62
	s_waitcnt lgkmcnt(0)
	v_cvt_pk_bf16_f32 v33, v64, v66
	v_cvt_pk_bf16_f32 v34, v55, v53
	v_cvt_pk_bf16_f32 v35, v57, v59
	v_cvt_pk_bf16_f32 v36, v61, v63
	v_cvt_pk_bf16_f32 v37, v65, v67
	global_store_dwordx4 v[38:39], v[22:25], off sc1
	global_store_dwordx4 v[40:41], v[26:29], off sc1
	global_store_dwordx4 v[42:43], v[30:33], off sc1
	global_store_dwordx4 v[44:45], v[34:37], off sc1
	s_waitcnt lgkmcnt(0)
	s_cbranch_scc1 .LBB0_675
